# shared selected-slot loop: hand-written softmax step (bias reads batched, permlane row max, one-fma exp2 argument), as the per-query loop
# speedup vs baseline: 1.0039x; 1.0039x over previous
; #define LAS __attribute__((address_space(3)))
; __device__ __forceinline__ float fexp(float x) { return __expf(x); }
; template <int MODE>
; __device__ __forceinline__ void softmax_half(f32x4 (&acc)[2], int base, bool ok, int t, int g4, const LAS float* lutg, SmState& st, f32x4 (&O)[4], bf16x8& pB) {
;     float mx = -1e30f; unsigned vm = 0u;
; #pragma unroll
;     for (int nt = 0; nt < 2; ++nt)
; #pragma unroll
;         for (int i = 0; i < 4; ++i) {
;             const int key = base + 16 * nt + 4 * g4 + i;
;             const int dist = t - key;
;             bool valid = dist >= 0;
;             if (MODE == 1) valid = valid && ok;
;             if (MODE == 2) valid = valid && dist < 512;
;             int dc = dist < 0 ? 0 : dist; dc = dc > 1023 ? 1023 : dc;
;             const float lg = acc[nt][i] + lutg[dc * 4];
;             acc[nt][i] = lg;
;             if (valid) { mx = fmaxf(mx, lg); vm |= 1u << (nt * 4 + i); }
;         }
;     mx = fmaxf(mx, __shfl_xor(mx, 16)); mx = fmaxf(mx, __shfl_xor(mx, 32));
;     const float mn = fmaxf(st.m, mx);
;     const float sc = fexp(st.m - mn);
;     float ls = 0.f;
; #pragma unroll
;     for (int nt = 0; nt < 2; ++nt)
; #pragma unroll
;         for (int i = 0; i < 4; ++i) { const float p = ((vm >> (nt * 4 + i)) & 1u) ? fexp(acc[nt][i] - mn) : 0.f; acc[nt][i] = p; ls += p; }
;     st.l = st.l * sc + ls; st.m = mn;
; __device__ __forceinline__ void nsa_wave(CArgs* Ap, int l, int b, int g, int tq0, const LAS float* lut, LAS float* imp, int lane) {
;     ...
;             for (int hs = 0; hs < 2 * ns; ++hs) {
;                 const int s = hs >> 1, hh = hs & 1;
;                 const int j = __builtin_amdgcn_readlane(selreg, s);
;                 const bool more = hs + 1 < 2 * ns; const int s1 = (hs + 1) >> 1, h1 = (hs + 1) & 1;
;                 const int jn = more ? __builtin_amdgcn_readlane(selreg, s1) : 0;
;                 f32x4 acc[2];
;                 acc[0] = (f32x4){0.f, 0.f, 0.f, 0.f}; acc[1] = (f32x4){0.f, 0.f, 0.f, 0.f};
;                 qk_acch8(acc, kh, q8);
;                 if (more) load_kh8(kh, Ks8 + (size_t)jn * 4096, h1, lane);
;                 if (__all(t - (j * 64 + 32 * hh + 31) >= 1023)) softmax_half_far(acc, lutg, st, Od);
;                 else { bf16x8 pB; softmax_half<1>(acc, j * 64 + 32 * hh, true, t, g4, lutg, st, Od, pB); }
.LBB0_1250:
	s_lshl_b32 s48, s50, 6
	s_and_b32 s49, s64, 32
	s_or_b32 s50, s48, s49
	v_subrev_u32_e32 v50, s50, v211
	v_cmp_lt_i32_e32 vcc, s75, v50
	s_cmp_eq_u64 vcc, exec
	s_cbranch_scc1 .Lssl_far
	v_or_b32_e32 v50, s50, v88
	v_sub_u32_e32 v144, v72, v50
	v_cmp_lt_i32_e32 vcc, 18, v144
	s_cmp_eq_u64 vcc, exec
	s_cbranch_scc1 .Lssl_um
	v_med3_i32 v51, v144, 0, v181
	v_lshl_add_u32 v51, v51, 4, v206
	ds_read_b32 v51, v51
	v_subrev_u32_e32 v53, 1, v144
	v_med3_i32 v53, v53, 0, v181
	v_lshl_add_u32 v53, v53, 4, v206
	ds_read_b32 v53, v53
	v_subrev_u32_e32 v54, 2, v144
	v_med3_i32 v54, v54, 0, v181
	v_lshl_add_u32 v54, v54, 4, v206
	ds_read_b32 v54, v54
	v_subrev_u32_e32 v55, 3, v144
	v_med3_i32 v55, v55, 0, v181
	v_lshl_add_u32 v55, v55, 4, v206
	ds_read_b32 v55, v55
	v_subrev_u32_e32 v56, 16, v144
	v_med3_i32 v56, v56, 0, v181
	v_lshl_add_u32 v56, v56, 4, v206
	ds_read_b32 v56, v56
	v_subrev_u32_e32 v57, 17, v144
	v_med3_i32 v57, v57, 0, v181
	v_lshl_add_u32 v57, v57, 4, v206
	ds_read_b32 v57, v57
	v_subrev_u32_e32 v58, 18, v144
	v_med3_i32 v58, v58, 0, v181
	v_lshl_add_u32 v58, v58, 4, v206
	ds_read_b32 v58, v58
	v_subrev_u32_e32 v59, 19, v144
	v_med3_i32 v59, v59, 0, v181
	v_lshl_add_u32 v59, v59, 4, v206
	ds_read_b32 v59, v59
	v_cmp_le_i32_e32 vcc, 0, v144
	v_cmp_le_i32_e64 s[48:49], 1, v144
	v_cmp_le_i32_e64 s[50:51], 2, v144
	v_cmp_le_i32_e64 s[52:53], 3, v144
	v_cmp_le_i32_e64 s[54:55], 16, v144
	v_cmp_le_i32_e64 s[56:57], 17, v144
	v_cmp_gt_i32_e64 s[58:59], 18, v144
	v_cmp_gt_i32_e64 s[60:61], 19, v144
	s_waitcnt lgkmcnt(7)
	v_add_f32_e32 v51, v28, v51
	v_max_f32_e32 v50, 0xf149f2ca, v51
	v_cndmask_b32_e32 v50, v182, v50, vcc
	s_waitcnt lgkmcnt(6)
	v_add_f32_e32 v53, v29, v53
	v_max_f32_e32 v52, v50, v53
	v_cndmask_b32_e64 v50, v50, v52, s[48:49]
	s_waitcnt lgkmcnt(5)
	v_add_f32_e32 v54, v30, v54
	v_max_f32_e32 v52, v50, v54
	v_cndmask_b32_e64 v50, v50, v52, s[50:51]
	s_waitcnt lgkmcnt(4)
	v_add_f32_e32 v55, v31, v55
	v_max_f32_e32 v52, v50, v55
	v_cndmask_b32_e64 v50, v50, v52, s[52:53]
	s_waitcnt lgkmcnt(3)
	v_add_f32_e32 v56, v24, v56
	v_max_f32_e32 v52, v50, v56
	v_cndmask_b32_e64 v50, v50, v52, s[54:55]
	s_waitcnt lgkmcnt(2)
	v_add_f32_e32 v57, v25, v57
	v_max_f32_e32 v52, v50, v57
	v_cndmask_b32_e64 v50, v50, v52, s[56:57]
	s_waitcnt lgkmcnt(1)
	v_add_f32_e32 v58, v26, v58
	v_max_f32_e32 v52, v50, v58
	v_cndmask_b32_e64 v50, v52, v50, s[58:59]
	s_waitcnt lgkmcnt(0)
	v_add_f32_e32 v59, v27, v59
	v_max_f32_e32 v52, v50, v59
	v_cndmask_b32_e64 v50, v52, v50, s[60:61]
	v_mov_b32_e32 v52, v50
	s_nop 1
	v_permlane16_swap_b32_e32 v50, v52
	v_max_f32_e32 v50, v50, v52
	v_mov_b32_e32 v52, v50
	s_nop 1
	v_permlane32_swap_b32_e32 v50, v52
	v_max3_f32 v144, v49, v50, v52
	v_mul_f32_e32 v212, 0xbfb8aa3b, v144
	v_add_f32_e32 v212, 0x41000000, v212
	v_fmamk_f32 v50, v51, 0x3fb8aa3b, v212
	v_fmamk_f32 v51, v53, 0x3fb8aa3b, v212
	v_fmamk_f32 v52, v54, 0x3fb8aa3b, v212
	v_fmamk_f32 v53, v55, 0x3fb8aa3b, v212
	v_fmamk_f32 v54, v56, 0x3fb8aa3b, v212
	v_fmamk_f32 v55, v57, 0x3fb8aa3b, v212
	v_fmamk_f32 v56, v58, 0x3fb8aa3b, v212
	v_fmamk_f32 v57, v59, 0x3fb8aa3b, v212
	v_exp_f32_e32 v50, v50
	v_exp_f32_e32 v51, v51
	v_exp_f32_e32 v52, v52
	v_exp_f32_e32 v53, v53
	v_exp_f32_e32 v54, v54
	v_exp_f32_e32 v55, v55
	v_exp_f32_e32 v56, v56
	v_exp_f32_e32 v57, v57
	v_cndmask_b32_e32 v50, 0, v50, vcc
	v_cndmask_b32_e64 v51, 0, v51, s[48:49]
	v_cndmask_b32_e64 v52, 0, v52, s[50:51]
	v_cndmask_b32_e64 v53, 0, v53, s[52:53]
	v_cndmask_b32_e64 v54, 0, v54, s[54:55]
	v_cndmask_b32_e64 v55, 0, v55, s[56:57]
	v_cndmask_b32_e64 v56, v56, 0, s[58:59]
	v_cndmask_b32_e64 v57, v57, 0, s[60:61]
	v_add_f32_e32 v58, v50, v51
	v_add_f32_e32 v59, v52, v53
	v_add_f32_e32 v212, v54, v55
	v_add_f32_e32 v24, v56, v57
	v_add_f32_e32 v58, v58, v59
	v_add_f32_e32 v212, v212, v24
	v_add_f32_e32 v58, v58, v212
	v_mul_f32_e32 v212, 0x3b800000, v58
	s_branch .Lssl_join
; #define LAS __attribute__((address_space(3)))
; __device__ __forceinline__ float fexp(float x) { return __expf(x); }
; __device__ __forceinline__ void softmax_half_far(f32x4 (&acc)[2], const LAS float* lutg, SmState& st, f32x4 (&O)[4]) {
;     const float bias = lutg[1023 * 4];
;     float mx = -1e30f;
; #pragma unroll
;     for (int nt = 0; nt < 2; ++nt)
; #pragma unroll
;         for (int i = 0; i < 4; ++i) { const float lg = acc[nt][i] + bias; acc[nt][i] = lg; mx = fmaxf(mx, lg); }
;     mx = fmaxf(mx, __shfl_xor(mx, 16)); mx = fmaxf(mx, __shfl_xor(mx, 32));
;     const float mn = fmaxf(st.m, mx);
;     const float sc = fexp(st.m - mn);
;     float ls = 0.f;
; #pragma unroll
;     for (int nt = 0; nt < 2; ++nt)
; #pragma unroll
;         for (int i = 0; i < 4; ++i) { const float p = fexp(acc[nt][i] - mn); acc[nt][i] = p; ls += p; }
;     st.l = st.l * sc + ls; st.m = mn;
; #pragma unroll
;     for (int dt = 0; dt < 4; ++dt) O[dt] = O[dt] * sc;
; }
; __device__ __forceinline__ void nsa_wave(CArgs* Ap, int l, int b, int g, int tq0, const LAS float* lut, LAS float* imp, int lane) {
;     ...
;                 qk_acch8(acc, kh, q8);
;                 if (more) load_kh8(kh, Ks8 + (size_t)jn * 4096, h1, lane);
;                 if (__all(t - (j * 64 + 32 * hh + 31) >= 1023)) softmax_half_far(acc, lutg, st, Od);
;                 else { bf16x8 pB; softmax_half<1>(acc, j * 64 + 32 * hh, true, t, g4, lutg, st, Od, pB); }
;                 pv_acch8(Od, vh, p_to_fp8(acc));
;                 if (more) load_vh8(vh, Vs8 + (size_t)jn * 4096, h1, lane);
.Lssl_um:
	v_min_i32_e32 v50, v181, v144
	v_lshl_add_u32 v50, v50, 4, v206
	ds_read_b32 v50, v50
	v_subrev_u32_e32 v51, 1, v144
	v_min_i32_e32 v51, v181, v51
	v_lshl_add_u32 v51, v51, 4, v206
	ds_read_b32 v51, v51
	v_subrev_u32_e32 v52, 2, v144
	v_min_i32_e32 v52, v181, v52
	v_lshl_add_u32 v52, v52, 4, v206
	ds_read_b32 v52, v52
	v_subrev_u32_e32 v53, 3, v144
	v_min_i32_e32 v53, v181, v53
	v_lshl_add_u32 v53, v53, 4, v206
	ds_read_b32 v53, v53
	v_subrev_u32_e32 v54, 16, v144
	v_min_i32_e32 v54, v181, v54
	v_lshl_add_u32 v54, v54, 4, v206
	ds_read_b32 v54, v54
	v_subrev_u32_e32 v55, 17, v144
	v_min_i32_e32 v55, v181, v55
	v_lshl_add_u32 v55, v55, 4, v206
	ds_read_b32 v55, v55
	v_subrev_u32_e32 v56, 18, v144
	v_min_i32_e32 v56, v181, v56
	v_lshl_add_u32 v56, v56, 4, v206
	ds_read_b32 v56, v56
	v_subrev_u32_e32 v57, 19, v144
	v_min_i32_e32 v57, v181, v57
	v_lshl_add_u32 v57, v57, 4, v206
	ds_read_b32 v57, v57
	s_waitcnt lgkmcnt(7)
	v_add_f32_e32 v28, v28, v50
	s_waitcnt lgkmcnt(6)
	v_add_f32_e32 v29, v29, v51
	s_waitcnt lgkmcnt(5)
	v_add_f32_e32 v30, v30, v52
	s_waitcnt lgkmcnt(4)
	v_add_f32_e32 v31, v31, v53
	s_waitcnt lgkmcnt(3)
	v_add_f32_e32 v24, v24, v54
	s_waitcnt lgkmcnt(2)
	v_add_f32_e32 v25, v25, v55
	s_waitcnt lgkmcnt(1)
	v_add_f32_e32 v26, v26, v56
	s_waitcnt lgkmcnt(0)
	v_add_f32_e32 v27, v27, v57
	v_max3_f32 v58, v28, s74, v29
	v_max3_f32 v58, v58, v30, v31
	v_max3_f32 v58, v58, v24, v25
	v_max3_f32 v58, v58, v26, v27
	v_mov_b32_e32 v59, v58
	s_nop 1
	v_permlane16_swap_b32_e32 v58, v59
	v_max_f32_e32 v58, v58, v59
	v_mov_b32_e32 v59, v58
	s_nop 1
	v_permlane32_swap_b32_e32 v58, v59
	v_max3_f32 v144, v49, v58, v59
	v_mul_f32_e32 v212, 0xbfb8aa3b, v144
	v_add_f32_e32 v212, 0x41000000, v212
	v_fmamk_f32 v50, v28, 0x3fb8aa3b, v212
	v_fmamk_f32 v51, v29, 0x3fb8aa3b, v212
	v_fmamk_f32 v52, v30, 0x3fb8aa3b, v212
	v_fmamk_f32 v53, v31, 0x3fb8aa3b, v212
	v_fmamk_f32 v54, v24, 0x3fb8aa3b, v212
	v_fmamk_f32 v55, v25, 0x3fb8aa3b, v212
	v_fmamk_f32 v56, v26, 0x3fb8aa3b, v212
	v_fmamk_f32 v57, v27, 0x3fb8aa3b, v212
	v_exp_f32_e32 v50, v50
	v_exp_f32_e32 v51, v51
	v_exp_f32_e32 v52, v52
	v_exp_f32_e32 v53, v53
	v_exp_f32_e32 v54, v54
	v_exp_f32_e32 v55, v55
	v_exp_f32_e32 v56, v56
	v_exp_f32_e32 v57, v57
	v_add_f32_e32 v58, v50, v51
	v_add_f32_e32 v59, v52, v53
	v_add_f32_e32 v212, v54, v55
	v_add_f32_e32 v24, v56, v57
	v_add_f32_e32 v58, v58, v59
	v_add_f32_e32 v212, v212, v24
	v_add_f32_e32 v58, v58, v212
	v_mul_f32_e32 v212, 0x3b800000, v58
	s_branch .Lssl_join
.Lssl_far:
	ds_read_b32 v50, v206 offset:16368
	s_waitcnt lgkmcnt(0)
	v_add_f32_e32 v28, v28, v50
	v_add_f32_e32 v29, v29, v50
	v_add_f32_e32 v30, v30, v50
	v_add_f32_e32 v31, v31, v50
	v_add_f32_e32 v24, v24, v50
	v_add_f32_e32 v25, v25, v50
	v_add_f32_e32 v26, v26, v50
	v_add_f32_e32 v27, v27, v50
	v_max3_f32 v58, v28, s74, v29
	v_max3_f32 v58, v58, v30, v31
	v_max3_f32 v58, v58, v24, v25
	v_max3_f32 v58, v58, v26, v27
	v_mov_b32_e32 v59, v58
	s_nop 1
	v_permlane16_swap_b32_e32 v58, v59
	v_max_f32_e32 v58, v58, v59
	v_mov_b32_e32 v59, v58
	s_nop 1
	v_permlane32_swap_b32_e32 v58, v59
	v_max3_f32 v144, v49, v58, v59
	v_mul_f32_e32 v212, 0xbfb8aa3b, v144
	v_add_f32_e32 v212, 0x41000000, v212
	v_fmamk_f32 v50, v28, 0x3fb8aa3b, v212
	v_fmamk_f32 v51, v29, 0x3fb8aa3b, v212
	v_fmamk_f32 v52, v30, 0x3fb8aa3b, v212
	v_fmamk_f32 v53, v31, 0x3fb8aa3b, v212
	v_fmamk_f32 v54, v24, 0x3fb8aa3b, v212
	v_fmamk_f32 v55, v25, 0x3fb8aa3b, v212
	v_fmamk_f32 v56, v26, 0x3fb8aa3b, v212
	v_fmamk_f32 v57, v27, 0x3fb8aa3b, v212
	v_exp_f32_e32 v50, v50
	v_exp_f32_e32 v51, v51
	v_exp_f32_e32 v52, v52
	v_exp_f32_e32 v53, v53
	v_exp_f32_e32 v54, v54
	v_exp_f32_e32 v55, v55
	v_exp_f32_e32 v56, v56
	v_exp_f32_e32 v57, v57
	v_add_f32_e32 v58, v50, v51
	v_add_f32_e32 v59, v52, v53
	v_add_f32_e32 v212, v54, v55
	v_add_f32_e32 v24, v56, v57
	v_add_f32_e32 v58, v58, v59
	v_add_f32_e32 v212, v212, v24
	v_add_f32_e32 v58, v58, v212
	v_mul_f32_e32 v212, 0x3b800000, v58
.Lssl_join:
	v_sub_f32_e32 v24, v49, v144
	v_cvt_pk_fp8_f32 v26, v50, v51
	v_mul_f32_e32 v24, 0x3fb8aa3b, v24
	v_cvt_pk_fp8_f32 v27, v54, v55
	v_exp_f32_e32 v24, v24
	v_cvt_pk_fp8_f32 v26, v52, v53 op_sel:[0,0,1]
	v_cvt_pk_fp8_f32 v27, v56, v57 op_sel:[0,0,1]
	v_pk_mul_f32 v[22:23], v[22:23], v[24:25] op_sel_hi:[1,0]
	v_pk_mul_f32 v[20:21], v[20:21], v[24:25] op_sel_hi:[1,0]
	v_pk_mul_f32 v[18:19], v[18:19], v[24:25] op_sel_hi:[1,0]
	v_pk_mul_f32 v[16:17], v[16:17], v[24:25] op_sel_hi:[1,0]
	v_pk_mul_f32 v[14:15], v[14:15], v[24:25] op_sel_hi:[1,0]
	v_pk_mul_f32 v[12:13], v[12:13], v[24:25] op_sel_hi:[1,0]
	v_pk_mul_f32 v[10:11], v[10:11], v[24:25] op_sel_hi:[1,0]
	v_pk_mul_f32 v[8:9], v[8:9], v[24:25] op_sel_hi:[1,0]
	s_waitcnt vmcnt(1)
	v_mfma_f32_16x16x32_fp8_fp8 v[20:23], v[40:41], v[26:27], v[20:23]
	s_and_b64 vcc, exec, s[46:47]
	s_nop 0
	v_mfma_f32_16x16x32_fp8_fp8 v[16:19], v[42:43], v[26:27], v[16:19]
	s_waitcnt vmcnt(0)
	v_mfma_f32_16x16x32_fp8_fp8 v[12:15], v[44:45], v[26:27], v[12:15]
	s_nop 0
	v_mfma_f32_16x16x32_fp8_fp8 v[8:11], v[46:47], v[26:27], v[8:11]
	s_cbranch_vccnz .LBB0_1256
	s_add_u32 s46, s0, s62
	s_addc_u32 s47, s1, s63
	v_lshl_or_b32 v25, s66, 11, v84
	global_load_dwordx4 v[40:43], v25, s[46:47]
	global_load_dwordx4 v[44:47], v25, s[46:47] offset:1024
